# EpiResid 16-byte sc1 store merge extended to FFN2-out (fp16 path)
# speedup vs baseline: 1.0163x; 1.0057x over previous
.LBB0_2014:
	global_load_dword v16, v1, s[6:7] sc1
	global_load_dword v0, v1, s[12:13] sc1
	s_waitcnt lgkmcnt(0)
	global_load_dword v2, v1, s[14:15] sc1
	global_load_dword v3, v1, s[16:17] sc1
	global_load_dword v4, v1, s[18:19] sc1
	global_load_dword v5, v1, s[20:21] sc1
	global_load_dword v6, v1, s[22:23] sc1
	global_load_dword v7, v1, s[24:25] sc1
	global_load_dword v8, v1, s[26:27] sc1
	global_load_dword v9, v1, s[28:29] sc1
	global_load_dword v10, v1, s[30:31] sc1
	global_load_dword v11, v1, s[34:35] sc1
	global_load_dword v12, v1, s[36:37] sc1
	global_load_dword v13, v1, s[38:39] sc1
	global_load_dword v14, v1, s[40:41] sc1
	global_load_dword v15, v1, s[42:43] sc1
	s_mov_b64 s[44:45], -1
	s_mov_b64 s[46:47], -1
	s_waitcnt vmcnt(9)
	v_add_u32_e32 v17, v0, v16
	s_waitcnt vmcnt(9)
	v_add_u32_e32 v17, v17, v2
	s_waitcnt vmcnt(8)
	v_add_u32_e32 v17, v17, v3
	s_waitcnt vmcnt(7)
	v_add_u32_e32 v17, v17, v4
	s_waitcnt vmcnt(6)
	v_add_u32_e32 v17, v17, v5
	s_waitcnt vmcnt(5)
	v_add_u32_e32 v17, v17, v6
	s_waitcnt vmcnt(4)
	v_add_u32_e32 v17, v17, v7
	s_waitcnt vmcnt(4)
	v_add_u32_e32 v17, v17, v8
	s_waitcnt vmcnt(3)
	v_add_u32_e32 v17, v17, v9
	s_waitcnt vmcnt(3)
	v_add_u32_e32 v17, v17, v10
	s_waitcnt vmcnt(2)
	v_add_u32_e32 v17, v17, v11
	s_waitcnt vmcnt(2)
	v_add_u32_e32 v17, v17, v12
	s_waitcnt vmcnt(1)
	v_add_u32_e32 v17, v17, v13
	s_waitcnt vmcnt(1)
	v_add_u32_e32 v17, v17, v14
	s_waitcnt vmcnt(0)
	v_add_u32_e32 v17, v17, v15
	v_cmp_eq_u32_e32 vcc, s62, v17
	s_cbranch_vccnz .LBB0_2013
	s_and_b32 s44, s51, 0xff
	s_cmp_eq_u32 s44, 0
	s_mov_b64 s[44:45], -1
	s_mov_b64 s[48:49], -1
	s_sleep 1
	s_cbranch_scc1 .LBB0_2018
	s_and_b64 vcc, exec, s[48:49]
	s_cbranch_vccz .LBB0_2013

.LBB0_2066:
	s_mov_b32 s28, s81
	v_mov_b32_e32 v0, v1
	s_getreg_b32 s0, hwreg(HW_REG_HW_ID, 0, 6)
	s_lshl_b32 s0, s0, 2
	s_and_b32 s0, s0, 0xfc
	v_add_u32_e32 v2, s0, v0
	v_add_u32_e32 v2, 0x24800, v2
	ds_read_b32 v2, v2
	v_mbcnt_lo_u32_b32 v0, -1, v0
	v_mbcnt_hi_u32_b32 v15, -1, v0
	s_cmpk_gt_i32 s28, 0x57f
	s_waitcnt lgkmcnt(0)
	v_readfirstlane_b32 s0, v2
	s_nop 1
	v_lshl_add_u32 v2, s0, 6, v15
	s_nop 0
	v_readfirstlane_b32 s1, v2
	s_cbranch_scc1 .LBB0_2082
	v_lshlrev_b32_e32 v3, 4, v2
	v_add_u32_e32 v4, 0x2000, v3
	v_ashrrev_i32_e32 v0, 31, v4
	v_lshrrev_b32_e32 v0, 22, v0
	v_add_u32_e32 v0, v4, v0
	v_ashrrev_i32_e32 v0, 10, v0
	v_mul_i32_i24_e32 v5, 0x400, v0
	v_sub_u32_e32 v4, v4, v5
	v_lshrrev_b32_e32 v5, 4, v4
	v_bitop3_b32 v4, v5, v4, 32 bitop3:0x6c
	v_ashrrev_i32_e32 v5, 31, v4
	v_lshrrev_b32_e32 v5, 26, v5
	v_add_u32_e32 v5, v4, v5
	v_lshlrev_b32_e32 v6, 3, v0
	v_readlane_b32 s0, v254, 55
	v_ashrrev_i32_e32 v10, 6, v5
	v_and_b32_e32 v6, -16, v6
	s_add_u32 s29, s0, 0x2200000
	v_readlane_b32 s0, v254, 56
	v_add_u32_e32 v6, v10, v6
	s_addc_u32 s30, s0, 0
	v_and_b32_e32 v7, 3, v10
	s_mov_b32 s0, 0x1fffe0
	v_lshrrev_b32_e32 v8, 2, v6
	v_lshlrev_b32_e32 v9, 1, v6
	v_and_b32_e32 v5, 0xc0, v5
	v_and_or_b32 v7, v6, s0, v7
	v_and_b32_e32 v8, 4, v8
	v_and_b32_e32 v9, 24, v9
	v_sub_u32_e32 v4, v4, v5
	v_or3_b32 v7, v7, v8, v9
	v_lshlrev_b32_e32 v8, 5, v0
	v_ashrrev_i16_sdwa v4, v232, sext(v4) dst_sel:DWORD dst_unused:UNUSED_PAD src0_sel:DWORD src1_sel:BYTE_0
	v_and_b32_e32 v8, 32, v8
	v_bfe_i32 v11, v4, 0, 16
	v_add_lshl_u32 v4, v8, v11, 1
	s_waitcnt vmcnt(4)
	v_lshl_add_u32 v150, v7, 11, v4
	v_lshl_add_u32 v152, v6, 11, v4
	v_bfe_i32 v4, v2, 27, 1
	v_lshrrev_b32_e32 v4, 22, v4
	v_add_u32_e32 v4, v3, v4
	v_and_b32_e32 v4, 0xfffffc00, v4
	v_sub_u32_e32 v3, v3, v4
	v_lshrrev_b32_e32 v4, 4, v3
	v_ashrrev_i32_e32 v5, 31, v2
	v_bitop3_b32 v3, v4, v3, 32 bitop3:0x6c
	v_lshrrev_b32_e32 v5, 26, v5
	v_ashrrev_i32_e32 v4, 31, v3
	v_add_u32_e32 v2, v2, v5
	v_lshrrev_b32_e32 v4, 26, v4
	v_ashrrev_i32_e32 v13, 6, v2
	v_add_u32_e32 v4, v3, v4
	v_lshlrev_b32_e32 v2, 3, v13
	v_ashrrev_i32_e32 v12, 6, v4
	v_and_b32_e32 v2, -16, v2
	v_add_u32_e32 v2, v12, v2
	v_and_b32_e32 v5, 3, v12
	s_ashr_i32 s34, s28, 31
	v_and_or_b32 v5, v2, s0, v5
	s_lshr_b32 s0, s34, 29
	s_add_i32 s0, s28, s0
	s_ashr_i32 s6, s1, 6
	s_ashr_i32 s4, s0, 3
	s_and_b32 s0, s0, -8
	s_ashr_i32 s7, s1, 8
	s_lshl_b32 s31, s6, 10
	s_sub_i32 s0, s28, s0
	s_cmp_lt_i32 s0, 0
	s_cselect_b32 s5, s57, 0xb0
	s_mul_i32 s0, s0, s5
	s_add_i32 s0, s0, s4
	s_mul_hi_i32 s4, s0, 0x2e8ba2e9
	s_lshr_b32 s5, s4, 31
	s_ashr_i32 s4, s4, 5
	s_add_i32 s4, s4, s5
	s_lshl_b32 s5, s4, 3
	s_mulk_i32 s4, 0xb0
	s_sub_i32 s4, s0, s4
	s_bfe_u32 s0, s4, 0x3001c
	s_add_i32 s12, s4, s0
	s_sext_i32_i16 s0, s12
	s_and_b32 s12, s12, 0xfff8
	s_sub_i32 s4, s4, s12
	s_sext_i32_i16 s4, s4
	v_lshrrev_b32_e32 v6, 2, v2
	v_lshlrev_b32_e32 v7, 1, v2
	v_and_b32_e32 v4, 0xc0, v4
	s_lshr_b32 s0, s0, 3
	s_add_i32 s20, s5, s4
	v_and_b32_e32 v6, 4, v6
	v_and_b32_e32 v7, 24, v7
	v_sub_u32_e32 v3, v3, v4
	s_ashr_i32 s21, s20, 31
	s_bfe_i64 s[12:13], s[0:1], 0x100000
	v_or3_b32 v5, v5, v6, v7
	v_lshlrev_b32_e32 v6, 5, v13
	v_ashrrev_i16_sdwa v3, v232, sext(v3) dst_sel:DWORD dst_unused:UNUSED_PAD src0_sel:DWORD src1_sel:BYTE_0
	s_lshl_b64 s[4:5], s[20:21], 19
	s_lshl_b64 s[12:13], s[12:13], 19
	v_and_b32_e32 v6, 32, v6
	v_bfe_i32 v14, v3, 0, 16
	s_add_u32 s24, s29, s12
	v_add_lshl_u32 v3, v6, v14, 1
	s_addc_u32 s25, s30, s13
	s_add_i32 s35, s31, 0
	v_lshl_add_u32 v154, v5, 11, v3
	s_add_i32 m0, s35, 0x10000
	v_lshl_add_u32 v156, v2, 11, v3
	global_load_lds_dwordx4 v154, s[24:25]
	s_add_i32 m0, s35, 0x12000
	s_add_u32 s12, s24, 0x40000
	global_load_lds_dwordx4 v150, s[24:25]
	s_addc_u32 s13, s25, 0
	s_add_i32 m0, s35, 0x14000
	v_mov_b32_e32 v155, v1
	global_load_lds_dwordx4 v154, s[12:13]
	s_add_i32 m0, s35, 0x16000
	s_add_u32 s22, s2, s4
	s_addc_u32 s23, s3, s5
	s_add_i32 s36, s35, 0x2000
	global_load_lds_dwordx4 v150, s[12:13]
	s_mov_b32 m0, s35
	s_add_u32 s4, s22, 0x40000
	global_load_lds_dwordx4 v156, s[22:23]
	s_mov_b32 m0, s36
	s_addc_u32 s5, s23, 0
	s_add_i32 s37, s35, 0x4000
	global_load_lds_dwordx4 v152, s[22:23]
	s_mov_b32 m0, s37
	s_add_i32 s38, s35, 0x6000
	global_load_lds_dwordx4 v156, s[4:5]
	s_mov_b32 m0, s38
	v_mov_b32_e32 v151, v1
	global_load_lds_dwordx4 v152, s[4:5]
	v_mov_b32_e32 v157, v1
	v_mov_b32_e32 v153, v1
	s_cmp_eq_u32 s7, 1
	v_mov_b64_e32 v[242:243], 0xff
	v_lshl_add_u64 v[8:9], s[24:25], 0, v[154:155]
	v_lshl_add_u64 v[6:7], s[24:25], 0, v[150:151]
	v_lshl_add_u64 v[2:3], s[22:23], 0, v[156:157]
	s_cselect_b64 s[4:5], -1, 0
	s_cmp_lg_u32 s7, 1
	v_lshl_add_u64 v[4:5], s[22:23], 0, v[152:153]
	s_cbranch_scc1 .LBB0_2069
	s_barrier

.LBB0_2476:
	s_mov_b32 s23, s33
	s_ashr_i32 s23, s22, 31
	s_lshl_b64 s[22:23], s[22:23], 8
	v_lshl_or_b32 v138, s47, 8, v165
	v_lshl_add_u64 v[140:141], s[22:23], 0, v[132:133]
	v_ashrrev_i32_e32 v139, 31, v138
	v_lshlrev_b64 v[144:145], 11, v[140:141]
	v_lshl_add_u64 v[142:143], s[6:7], 0, v[144:145]
	v_lshlrev_b64 v[146:147], 1, v[138:139]
	s_mov_b32 s24, s33
	v_lshl_add_u64 v[142:143], v[142:143], 0, v[146:147]
	global_load_dwordx2 v[168:169], v[142:143], off
	global_load_dwordx2 v[162:163], v[142:143], off offset:32
	global_load_dwordx2 v[160:161], v[142:143], off offset:256
	global_load_dwordx2 v[156:157], v[142:143], off offset:288
	v_lshl_add_u64 v[142:143], s[6:7], 0, v[146:147]
	v_lshl_add_u64 v[144:145], v[142:143], 0, v[144:145]
	v_add_co_u32_e32 v146, vcc, s54, v144
	v_mov_b32_e32 v154, s24
	s_nop 0
	v_addc_co_u32_e32 v147, vcc, 0, v145, vcc
	global_load_dwordx2 v[152:153], v[146:147], off
	global_load_dwordx2 v[150:151], v[146:147], off offset:32
	global_load_dwordx2 v[148:149], v[146:147], off offset:256
	s_nop 0
	global_load_dwordx2 v[146:147], v[146:147], off offset:288
	ds_read2_b32 v[170:171], v154 offset1:1
	v_lshlrev_b64 v[154:155], 10, v[140:141]
	v_lshl_add_u64 v[158:159], v[154:155], 0, v[138:139]
	s_mov_b64 s[6:7], -1
	s_and_b64 vcc, exec, s[10:11]
	v_lshl_add_u64 v[154:155], v[158:159], 1, s[20:21]
	s_waitcnt lgkmcnt(0)
	v_readfirstlane_b32 s24, v170
	v_readfirstlane_b32 s25, v171
	s_waitcnt vmcnt(0)
	v_cvt_f32_f16_e32 v172, v168
	v_cvt_f32_f16_e32 v174, v169
	v_cvt_f32_f16_sdwa v175, v169 dst_sel:DWORD dst_unused:UNUSED_PAD src0_sel:WORD_1
	v_cvt_f32_f16_sdwa v173, v168 dst_sel:DWORD dst_unused:UNUSED_PAD src0_sel:WORD_1
	v_pk_fma_f32 v[128:129], v[128:129], 0.5, v[174:175] op_sel_hi:[1,0,1]
	v_pk_fma_f32 v[126:127], v[126:127], 0.5, v[172:173] op_sel_hi:[1,0,1]
	s_cbranch_vccz .LBB0_2478
	v_cvt_f16_f32_e32 v167, v126
	v_cvt_f16_f32_sdwa v168, v127 dst_sel:WORD_1 dst_unused:UNUSED_PAD src0_sel:DWORD
	v_cvt_f16_f32_e32 v169, v128
	v_cvt_f16_f32_sdwa v170, v129 dst_sel:WORD_1 dst_unused:UNUSED_PAD src0_sel:DWORD
	s_mov_b64 s[6:7], 0
	v_or_b32_e32 v168, v168, v167
	v_or_b32_e32 v169, v170, v169
	v_mov_b32_e32 v240, v168
	v_mov_b32_e32 v241, v169
	v_pk_mul_f32 v[168:169], v[128:129], v[128:129]
	v_pk_mul_f32 v[170:171], v[126:127], v[126:127]
	s_nop 0
	v_pk_mov_b32 v[172:173], v[170:171], v[168:169] op_sel:[1,0]
	v_mov_b32_e32 v171, v169
	v_pk_add_f32 v[168:169], v[172:173], v[170:171]
	s_nop 0
	v_add_f32_e32 v167, v168, v169

.LBB0_2480:
	s_nop 1
	v_cvt_f32_f16_sdwa v127, v162 dst_sel:DWORD dst_unused:UNUSED_PAD src0_sel:WORD_1
	v_cvt_f32_f16_e32 v126, v162
	v_cvt_f32_f16_sdwa v129, v163 dst_sel:DWORD dst_unused:UNUSED_PAD src0_sel:WORD_1
	v_cvt_f32_f16_e32 v128, v163
	s_andn2_b64 vcc, exec, s[10:11]
	v_pk_fma_f32 v[122:123], v[122:123], 0.5, v[126:127] op_sel_hi:[1,0,1]
	v_cndmask_b32_e64 v126, 0, 1, s[10:11]
	v_pk_fma_f32 v[124:125], v[124:125], 0.5, v[128:129] op_sel_hi:[1,0,1]
	v_cmp_ne_u32_e64 s[6:7], 1, v126
	s_mov_b64 s[22:23], -1
	s_cbranch_vccnz .LBB0_2482
	v_cvt_f16_f32_e32 v126, v122
	v_cvt_f16_f32_sdwa v127, v123 dst_sel:WORD_1 dst_unused:UNUSED_PAD src0_sel:DWORD
	v_cvt_f16_f32_e32 v128, v124
	v_cvt_f16_f32_sdwa v129, v125 dst_sel:WORD_1 dst_unused:UNUSED_PAD src0_sel:DWORD
	s_mov_b64 s[22:23], 0
	v_or_b32_e32 v126, v127, v126
	v_or_b32_e32 v127, v129, v128
	v_mov_b32_e32 v242, v126
	v_mov_b32_e32 v243, v127
	v_mbcnt_lo_u32_b32 v222, -1, 0
	v_mbcnt_hi_u32_b32 v222, -1, v222
	v_bfe_u32 v222, v222, 4, 1
	v_mul_u32_u24_e32 v222, 24, v222
	v_mov_b32_e32 v223, 0
	v_permlane16_swap_b32_e32 v240, v242
	v_permlane16_swap_b32_e32 v241, v243
	v_lshl_add_u64 v[222:223], v[154:155], 0, v[222:223]
	global_store_dwordx4 v[222:223], v[240:243], off sc1
	v_pk_mul_f32 v[126:127], v[124:125], v[124:125]
	v_pk_mul_f32 v[128:129], v[122:123], v[122:123]
	s_nop 0
	v_pk_mov_b32 v[162:163], v[128:129], v[126:127] op_sel:[1,0]
	v_mov_b32_e32 v129, v127
	v_pk_add_f32 v[126:127], v[162:163], v[128:129]
	s_nop 0
	v_add_f32_e32 v126, v126, v127
	v_add_f32_e32 v126, v126, v167

.LBB0_2484:
	s_nop 1
	v_cvt_f32_f16_sdwa v123, v160 dst_sel:DWORD dst_unused:UNUSED_PAD src0_sel:WORD_1
	v_cvt_f32_f16_sdwa v125, v161 dst_sel:DWORD dst_unused:UNUSED_PAD src0_sel:WORD_1
	v_cvt_f32_f16_e32 v124, v161
	v_cvt_f32_f16_e32 v122, v160
	s_and_b64 vcc, exec, s[6:7]
	s_mov_b64 s[22:23], -1
	v_pk_fma_f32 v[120:121], v[120:121], 0.5, v[124:125] op_sel_hi:[1,0,1]
	v_pk_fma_f32 v[118:119], v[118:119], 0.5, v[122:123] op_sel_hi:[1,0,1]
	s_cbranch_vccnz .LBB0_2486
	v_cvt_f16_f32_e32 v122, v118
	v_cvt_f16_f32_sdwa v123, v119 dst_sel:WORD_1 dst_unused:UNUSED_PAD src0_sel:DWORD
	v_cvt_f16_f32_e32 v124, v120
	v_cvt_f16_f32_sdwa v125, v121 dst_sel:WORD_1 dst_unused:UNUSED_PAD src0_sel:DWORD
	s_mov_b64 s[22:23], 0
	v_or_b32_e32 v122, v123, v122
	v_or_b32_e32 v123, v125, v124
	v_mov_b32_e32 v244, v122
	v_mov_b32_e32 v245, v123
	v_pk_mul_f32 v[122:123], v[120:121], v[120:121]
	v_pk_mul_f32 v[124:125], v[118:119], v[118:119]
	s_nop 0
	v_pk_mov_b32 v[128:129], v[124:125], v[122:123] op_sel:[1,0]
	v_mov_b32_e32 v125, v123
	v_pk_add_f32 v[122:123], v[128:129], v[124:125]
	s_nop 0
	v_add_f32_e32 v122, v122, v123
	v_add_f32_e32 v122, v122, v126

.LBB0_2488:
	s_nop 1
	v_cvt_f32_f16_sdwa v119, v156 dst_sel:DWORD dst_unused:UNUSED_PAD src0_sel:WORD_1
	v_cvt_f32_f16_sdwa v121, v157 dst_sel:DWORD dst_unused:UNUSED_PAD src0_sel:WORD_1
	v_cvt_f32_f16_e32 v120, v157
	v_cvt_f32_f16_e32 v118, v156
	s_and_b64 vcc, exec, s[6:7]
	s_mov_b64 s[22:23], -1
	v_pk_fma_f32 v[116:117], v[116:117], 0.5, v[120:121] op_sel_hi:[1,0,1]
	v_pk_fma_f32 v[114:115], v[114:115], 0.5, v[118:119] op_sel_hi:[1,0,1]
	s_cbranch_vccnz .LBB0_2490
	v_cvt_f16_f32_e32 v118, v114
	v_cvt_f16_f32_sdwa v119, v115 dst_sel:WORD_1 dst_unused:UNUSED_PAD src0_sel:DWORD
	v_cvt_f16_f32_sdwa v120, v117 dst_sel:WORD_1 dst_unused:UNUSED_PAD src0_sel:DWORD
	s_mov_b64 s[22:23], 0
	v_or_b32_e32 v118, v119, v118
	v_cvt_f16_f32_e32 v119, v116
	v_or_b32_e32 v119, v120, v119
	v_mov_b32_e32 v246, v118
	v_mov_b32_e32 v247, v119
	v_mbcnt_lo_u32_b32 v222, -1, 0
	v_mbcnt_hi_u32_b32 v222, -1, v222
	v_bfe_u32 v222, v222, 4, 1
	v_mul_u32_u24_e32 v222, 24, v222
	v_mov_b32_e32 v223, 0
	v_permlane16_swap_b32_e32 v244, v246
	v_permlane16_swap_b32_e32 v245, v247
	v_lshl_add_u64 v[222:223], v[154:155], 0, v[222:223]
	global_store_dwordx4 v[222:223], v[244:247], off offset:256 sc1
	v_pk_mul_f32 v[118:119], v[116:117], v[116:117]
	v_pk_mul_f32 v[120:121], v[114:115], v[114:115]
	s_nop 0
	v_pk_mov_b32 v[124:125], v[120:121], v[118:119] op_sel:[1,0]
	v_mov_b32_e32 v121, v119
	v_pk_add_f32 v[118:119], v[124:125], v[120:121]
	s_nop 0
	v_add_f32_e32 v118, v118, v119
	v_add_f32_e32 v118, v118, v122

.LBB0_2496:
	v_add_co_u32_e32 v114, vcc, 0x10000, v144
	v_cvt_f32_f16_sdwa v125, v152 dst_sel:DWORD dst_unused:UNUSED_PAD src0_sel:WORD_1
	s_waitcnt lgkmcnt(0)
	v_addc_co_u32_e32 v115, vcc, 0, v145, vcc
	global_load_dwordx2 v[120:121], v[114:115], off
	global_load_dwordx2 v[118:119], v[114:115], off offset:32
	global_load_dwordx2 v[116:117], v[114:115], off offset:256
	s_nop 0
	global_load_dwordx2 v[114:115], v[114:115], off offset:288
	v_cvt_f32_f16_e32 v124, v152
	v_cvt_f32_f16_sdwa v129, v153 dst_sel:DWORD dst_unused:UNUSED_PAD src0_sel:WORD_1
	v_cvt_f32_f16_e32 v128, v153
	v_or_b32_e32 v122, 16, v140
	v_mov_b32_e32 v123, v141
	v_lshlrev_b64 v[126:127], 10, v[122:123]
	v_lshl_add_u64 v[126:127], v[126:127], 0, v[138:139]
	v_pk_fma_f32 v[112:113], v[112:113], 0.5, v[128:129] op_sel_hi:[1,0,1]
	v_pk_fma_f32 v[110:111], v[110:111], 0.5, v[124:125] op_sel_hi:[1,0,1]
	s_mov_b64 s[24:25], -1
	s_and_b64 vcc, exec, s[6:7]
	v_lshl_add_u64 v[124:125], v[126:127], 1, s[20:21]
	s_cbranch_vccnz .LBB0_2498
	v_cvt_f16_f32_e32 v128, v110
	v_cvt_f16_f32_sdwa v129, v111 dst_sel:WORD_1 dst_unused:UNUSED_PAD src0_sel:DWORD
	v_cvt_f16_f32_e32 v152, v112
	v_cvt_f16_f32_sdwa v153, v113 dst_sel:WORD_1 dst_unused:UNUSED_PAD src0_sel:DWORD
	s_mov_b64 s[24:25], 0
	v_or_b32_e32 v128, v129, v128
	v_or_b32_e32 v129, v153, v152
	v_mov_b32_e32 v240, v128
	v_mov_b32_e32 v241, v129
	v_pk_mul_f32 v[128:129], v[112:113], v[112:113]
	v_pk_mul_f32 v[152:153], v[110:111], v[110:111]
	s_nop 0
	v_pk_mov_b32 v[154:155], v[152:153], v[128:129] op_sel:[1,0]
	v_mov_b32_e32 v153, v129
	v_pk_add_f32 v[128:129], v[154:155], v[152:153]
	s_nop 0
	v_add_f32_e32 v128, v128, v129

.LBB0_2500:
	s_nop 1
	v_cvt_f32_f16_sdwa v111, v150 dst_sel:DWORD dst_unused:UNUSED_PAD src0_sel:WORD_1
	v_cvt_f32_f16_sdwa v113, v151 dst_sel:DWORD dst_unused:UNUSED_PAD src0_sel:WORD_1
	v_cvt_f32_f16_e32 v112, v151
	v_cvt_f32_f16_e32 v110, v150
	s_and_b64 vcc, exec, s[6:7]
	s_mov_b64 s[24:25], -1
	v_pk_fma_f32 v[108:109], v[108:109], 0.5, v[112:113] op_sel_hi:[1,0,1]
	v_pk_fma_f32 v[106:107], v[106:107], 0.5, v[110:111] op_sel_hi:[1,0,1]
	s_cbranch_vccnz .LBB0_2502
	v_cvt_f16_f32_e32 v110, v106
	v_cvt_f16_f32_sdwa v111, v107 dst_sel:WORD_1 dst_unused:UNUSED_PAD src0_sel:DWORD
	v_cvt_f16_f32_e32 v112, v108
	v_cvt_f16_f32_sdwa v113, v109 dst_sel:WORD_1 dst_unused:UNUSED_PAD src0_sel:DWORD
	s_mov_b64 s[24:25], 0
	v_or_b32_e32 v110, v111, v110
	v_or_b32_e32 v111, v113, v112
	v_mov_b32_e32 v242, v110
	v_mov_b32_e32 v243, v111
	v_mbcnt_lo_u32_b32 v222, -1, 0
	v_mbcnt_hi_u32_b32 v222, -1, v222
	v_bfe_u32 v222, v222, 4, 1
	v_mul_u32_u24_e32 v222, 24, v222
	v_mov_b32_e32 v223, 0
	v_permlane16_swap_b32_e32 v240, v242
	v_permlane16_swap_b32_e32 v241, v243
	v_lshl_add_u64 v[222:223], v[124:125], 0, v[222:223]
	global_store_dwordx4 v[222:223], v[240:243], off sc1
	v_pk_mul_f32 v[110:111], v[108:109], v[108:109]
	v_pk_mul_f32 v[112:113], v[106:107], v[106:107]
	s_nop 0
	v_pk_mov_b32 v[150:151], v[112:113], v[110:111] op_sel:[1,0]
	v_mov_b32_e32 v113, v111
	v_pk_add_f32 v[110:111], v[150:151], v[112:113]
	s_nop 0
	v_add_f32_e32 v110, v110, v111
	v_add_f32_e32 v110, v110, v128

.LBB0_2504:
	s_nop 1
	v_cvt_f32_f16_sdwa v107, v148 dst_sel:DWORD dst_unused:UNUSED_PAD src0_sel:WORD_1
	v_cvt_f32_f16_sdwa v109, v149 dst_sel:DWORD dst_unused:UNUSED_PAD src0_sel:WORD_1
	v_cvt_f32_f16_e32 v108, v149
	v_cvt_f32_f16_e32 v106, v148
	s_and_b64 vcc, exec, s[6:7]
	s_mov_b64 s[24:25], -1
	v_pk_fma_f32 v[104:105], v[104:105], 0.5, v[108:109] op_sel_hi:[1,0,1]
	v_pk_fma_f32 v[102:103], v[102:103], 0.5, v[106:107] op_sel_hi:[1,0,1]
	s_cbranch_vccnz .LBB0_2506
	v_cvt_f16_f32_e32 v106, v102
	v_cvt_f16_f32_sdwa v107, v103 dst_sel:WORD_1 dst_unused:UNUSED_PAD src0_sel:DWORD
	v_cvt_f16_f32_e32 v108, v104
	v_cvt_f16_f32_sdwa v109, v105 dst_sel:WORD_1 dst_unused:UNUSED_PAD src0_sel:DWORD
	s_mov_b64 s[24:25], 0
	v_or_b32_e32 v106, v107, v106
	v_or_b32_e32 v107, v109, v108
	v_mov_b32_e32 v244, v106
	v_mov_b32_e32 v245, v107
	v_pk_mul_f32 v[106:107], v[104:105], v[104:105]
	v_pk_mul_f32 v[108:109], v[102:103], v[102:103]
	s_nop 0
	v_pk_mov_b32 v[112:113], v[108:109], v[106:107] op_sel:[1,0]
	v_mov_b32_e32 v109, v107
	v_pk_add_f32 v[106:107], v[112:113], v[108:109]
	s_nop 0
	v_add_f32_e32 v106, v106, v107
	v_add_f32_e32 v106, v106, v110

.LBB0_2508:
	s_nop 1
	v_cvt_f32_f16_sdwa v103, v146 dst_sel:DWORD dst_unused:UNUSED_PAD src0_sel:WORD_1
	v_cvt_f32_f16_sdwa v105, v147 dst_sel:DWORD dst_unused:UNUSED_PAD src0_sel:WORD_1
	v_cvt_f32_f16_e32 v104, v147
	v_cvt_f32_f16_e32 v102, v146
	s_and_b64 vcc, exec, s[6:7]
	s_mov_b64 s[24:25], -1
	v_pk_fma_f32 v[100:101], v[100:101], 0.5, v[104:105] op_sel_hi:[1,0,1]
	v_pk_fma_f32 v[98:99], v[98:99], 0.5, v[102:103] op_sel_hi:[1,0,1]
	s_cbranch_vccnz .LBB0_2511
	v_cvt_f16_f32_e32 v102, v98
	v_cvt_f16_f32_sdwa v103, v99 dst_sel:WORD_1 dst_unused:UNUSED_PAD src0_sel:DWORD
	v_cvt_f16_f32_sdwa v104, v101 dst_sel:WORD_1 dst_unused:UNUSED_PAD src0_sel:DWORD
	v_or_b32_e32 v102, v103, v102
	v_cvt_f16_f32_e32 v103, v100
	v_or_b32_e32 v103, v104, v103
	v_mov_b32_e32 v246, v102
	v_mov_b32_e32 v247, v103
	v_mbcnt_lo_u32_b32 v222, -1, 0
	v_mbcnt_hi_u32_b32 v222, -1, v222
	v_bfe_u32 v222, v222, 4, 1
	v_mul_u32_u24_e32 v222, 24, v222
	v_mov_b32_e32 v223, 0
	v_permlane16_swap_b32_e32 v244, v246
	v_permlane16_swap_b32_e32 v245, v247
	v_lshl_add_u64 v[222:223], v[124:125], 0, v[222:223]
	global_store_dwordx4 v[222:223], v[244:247], off offset:256 sc1
	v_pk_mul_f32 v[102:103], v[100:101], v[100:101]
	v_pk_mul_f32 v[104:105], v[98:99], v[98:99]
	s_nop 0
	v_pk_mov_b32 v[108:109], v[104:105], v[102:103] op_sel:[1,0]
	v_mov_b32_e32 v105, v103
	v_pk_add_f32 v[102:103], v[108:109], v[104:105]
	s_nop 0
	v_add_f32_e32 v102, v102, v103
	v_add_f32_e32 v102, v102, v106
	s_cbranch_execz .LBB0_2512

.LBB0_2516:
	v_add_co_u32_e32 v98, vcc, 0x18000, v144
	s_waitcnt vmcnt(2)
	v_cvt_f32_f16_sdwa v109, v120 dst_sel:DWORD dst_unused:UNUSED_PAD src0_sel:WORD_1
	s_waitcnt lgkmcnt(0)
	v_addc_co_u32_e32 v99, vcc, 0, v145, vcc
	global_load_dwordx2 v[104:105], v[98:99], off
	global_load_dwordx2 v[102:103], v[98:99], off offset:32
	global_load_dwordx2 v[100:101], v[98:99], off offset:256
	s_nop 0
	global_load_dwordx2 v[98:99], v[98:99], off offset:288
	v_cvt_f32_f16_e32 v108, v120
	v_cvt_f32_f16_sdwa v113, v121 dst_sel:DWORD dst_unused:UNUSED_PAD src0_sel:WORD_1
	v_cvt_f32_f16_e32 v112, v121
	v_or_b32_e32 v106, 32, v140
	v_mov_b32_e32 v107, v141
	v_lshlrev_b64 v[110:111], 10, v[106:107]
	v_lshl_add_u64 v[110:111], v[110:111], 0, v[138:139]
	v_pk_fma_f32 v[96:97], v[96:97], 0.5, v[112:113] op_sel_hi:[1,0,1]
	v_pk_fma_f32 v[94:95], v[94:95], 0.5, v[108:109] op_sel_hi:[1,0,1]
	s_mov_b64 s[24:25], -1
	s_and_b64 vcc, exec, s[6:7]
	v_lshl_add_u64 v[108:109], v[110:111], 1, s[20:21]
	s_cbranch_vccnz .LBB0_2518
	v_cvt_f16_f32_e32 v112, v94
	v_cvt_f16_f32_sdwa v113, v95 dst_sel:WORD_1 dst_unused:UNUSED_PAD src0_sel:DWORD
	v_cvt_f16_f32_e32 v120, v96
	v_cvt_f16_f32_sdwa v121, v97 dst_sel:WORD_1 dst_unused:UNUSED_PAD src0_sel:DWORD
	s_mov_b64 s[24:25], 0
	v_or_b32_e32 v112, v113, v112
	v_or_b32_e32 v113, v121, v120
	v_mov_b32_e32 v240, v112
	v_mov_b32_e32 v241, v113
	v_pk_mul_f32 v[112:113], v[96:97], v[96:97]
	v_pk_mul_f32 v[120:121], v[94:95], v[94:95]
	s_nop 0
	v_pk_mov_b32 v[122:123], v[120:121], v[112:113] op_sel:[1,0]
	v_mov_b32_e32 v121, v113
	v_pk_add_f32 v[112:113], v[122:123], v[120:121]
	s_nop 0
	v_add_f32_e32 v112, v112, v113

.LBB0_2520:
	s_waitcnt vmcnt(5)
	s_nop 0
	v_cvt_f32_f16_sdwa v95, v118 dst_sel:DWORD dst_unused:UNUSED_PAD src0_sel:WORD_1
	v_cvt_f32_f16_sdwa v97, v119 dst_sel:DWORD dst_unused:UNUSED_PAD src0_sel:WORD_1
	v_cvt_f32_f16_e32 v96, v119
	v_cvt_f32_f16_e32 v94, v118
	s_and_b64 vcc, exec, s[6:7]
	s_mov_b64 s[24:25], -1
	v_pk_fma_f32 v[92:93], v[92:93], 0.5, v[96:97] op_sel_hi:[1,0,1]
	v_pk_fma_f32 v[90:91], v[90:91], 0.5, v[94:95] op_sel_hi:[1,0,1]
	s_cbranch_vccnz .LBB0_2522
	v_cvt_f16_f32_e32 v94, v90
	v_cvt_f16_f32_sdwa v95, v91 dst_sel:WORD_1 dst_unused:UNUSED_PAD src0_sel:DWORD
	v_cvt_f16_f32_e32 v96, v92
	v_cvt_f16_f32_sdwa v97, v93 dst_sel:WORD_1 dst_unused:UNUSED_PAD src0_sel:DWORD
	s_mov_b64 s[24:25], 0
	v_or_b32_e32 v94, v95, v94
	v_or_b32_e32 v95, v97, v96
	v_mov_b32_e32 v242, v94
	v_mov_b32_e32 v243, v95
	v_mbcnt_lo_u32_b32 v222, -1, 0
	v_mbcnt_hi_u32_b32 v222, -1, v222
	v_bfe_u32 v222, v222, 4, 1
	v_mul_u32_u24_e32 v222, 24, v222
	v_mov_b32_e32 v223, 0
	v_permlane16_swap_b32_e32 v240, v242
	v_permlane16_swap_b32_e32 v241, v243
	v_lshl_add_u64 v[222:223], v[108:109], 0, v[222:223]
	global_store_dwordx4 v[222:223], v[240:243], off sc1
	v_pk_mul_f32 v[94:95], v[92:93], v[92:93]
	v_pk_mul_f32 v[96:97], v[90:91], v[90:91]
	s_nop 0
	v_pk_mov_b32 v[118:119], v[96:97], v[94:95] op_sel:[1,0]
	v_mov_b32_e32 v97, v95
	v_pk_add_f32 v[94:95], v[118:119], v[96:97]
	s_nop 0
	v_add_f32_e32 v94, v94, v95
	v_add_f32_e32 v94, v94, v112

.LBB0_2524:
	s_waitcnt vmcnt(4)
	s_nop 0
	v_cvt_f32_f16_sdwa v91, v116 dst_sel:DWORD dst_unused:UNUSED_PAD src0_sel:WORD_1
	v_cvt_f32_f16_sdwa v93, v117 dst_sel:DWORD dst_unused:UNUSED_PAD src0_sel:WORD_1
	v_cvt_f32_f16_e32 v92, v117
	v_cvt_f32_f16_e32 v90, v116
	s_and_b64 vcc, exec, s[6:7]
	s_mov_b64 s[24:25], -1
	v_pk_fma_f32 v[88:89], v[88:89], 0.5, v[92:93] op_sel_hi:[1,0,1]
	v_pk_fma_f32 v[86:87], v[86:87], 0.5, v[90:91] op_sel_hi:[1,0,1]
	s_cbranch_vccnz .LBB0_2526
	v_cvt_f16_f32_e32 v90, v86
	v_cvt_f16_f32_sdwa v91, v87 dst_sel:WORD_1 dst_unused:UNUSED_PAD src0_sel:DWORD
	v_cvt_f16_f32_e32 v92, v88
	v_cvt_f16_f32_sdwa v93, v89 dst_sel:WORD_1 dst_unused:UNUSED_PAD src0_sel:DWORD
	s_mov_b64 s[24:25], 0
	v_or_b32_e32 v90, v91, v90
	v_or_b32_e32 v91, v93, v92
	v_mov_b32_e32 v244, v90
	v_mov_b32_e32 v245, v91
	v_pk_mul_f32 v[90:91], v[88:89], v[88:89]
	v_pk_mul_f32 v[92:93], v[86:87], v[86:87]
	s_nop 0
	v_pk_mov_b32 v[96:97], v[92:93], v[90:91] op_sel:[1,0]
	v_mov_b32_e32 v93, v91
	v_pk_add_f32 v[90:91], v[96:97], v[92:93]
	s_nop 0
	v_add_f32_e32 v90, v90, v91
	v_add_f32_e32 v90, v90, v94

.LBB0_2528:
	s_waitcnt vmcnt(2)
	s_nop 0
	v_cvt_f32_f16_sdwa v87, v114 dst_sel:DWORD dst_unused:UNUSED_PAD src0_sel:WORD_1
	v_cvt_f32_f16_sdwa v89, v115 dst_sel:DWORD dst_unused:UNUSED_PAD src0_sel:WORD_1
	v_cvt_f32_f16_e32 v88, v115
	v_cvt_f32_f16_e32 v86, v114
	s_and_b64 vcc, exec, s[6:7]
	s_mov_b64 s[24:25], -1
	v_pk_fma_f32 v[84:85], v[84:85], 0.5, v[88:89] op_sel_hi:[1,0,1]
	v_pk_fma_f32 v[82:83], v[82:83], 0.5, v[86:87] op_sel_hi:[1,0,1]
	s_cbranch_vccnz .LBB0_2531
	v_cvt_f16_f32_e32 v86, v82
	v_cvt_f16_f32_sdwa v87, v83 dst_sel:WORD_1 dst_unused:UNUSED_PAD src0_sel:DWORD
	v_cvt_f16_f32_sdwa v88, v85 dst_sel:WORD_1 dst_unused:UNUSED_PAD src0_sel:DWORD
	v_or_b32_e32 v86, v87, v86
	v_cvt_f16_f32_e32 v87, v84
	v_or_b32_e32 v87, v88, v87
	v_mov_b32_e32 v246, v86
	v_mov_b32_e32 v247, v87
	v_mbcnt_lo_u32_b32 v222, -1, 0
	v_mbcnt_hi_u32_b32 v222, -1, v222
	v_bfe_u32 v222, v222, 4, 1
	v_mul_u32_u24_e32 v222, 24, v222
	v_mov_b32_e32 v223, 0
	v_permlane16_swap_b32_e32 v244, v246
	v_permlane16_swap_b32_e32 v245, v247
	v_lshl_add_u64 v[222:223], v[108:109], 0, v[222:223]
	global_store_dwordx4 v[222:223], v[244:247], off offset:256 sc1
	v_pk_mul_f32 v[86:87], v[84:85], v[84:85]
	v_pk_mul_f32 v[88:89], v[82:83], v[82:83]
	s_nop 0
	v_pk_mov_b32 v[92:93], v[88:89], v[86:87] op_sel:[1,0]
	v_mov_b32_e32 v89, v87
	v_pk_add_f32 v[86:87], v[92:93], v[88:89]
	s_nop 0
	v_add_f32_e32 v86, v86, v87
	v_add_f32_e32 v86, v86, v90
	s_cbranch_execz .LBB0_2532

.LBB0_2536:
	v_add_co_u32_e32 v82, vcc, 0x40000, v144
	s_waitcnt vmcnt(2)
	v_cvt_f32_f16_sdwa v93, v104 dst_sel:DWORD dst_unused:UNUSED_PAD src0_sel:WORD_1
	s_waitcnt lgkmcnt(0)
	v_addc_co_u32_e32 v83, vcc, 0, v145, vcc
	global_load_dwordx2 v[88:89], v[82:83], off
	global_load_dwordx2 v[86:87], v[82:83], off offset:32
	global_load_dwordx2 v[84:85], v[82:83], off offset:256
	s_nop 0
	global_load_dwordx2 v[82:83], v[82:83], off offset:288
	v_cvt_f32_f16_e32 v92, v104
	v_cvt_f32_f16_sdwa v97, v105 dst_sel:DWORD dst_unused:UNUSED_PAD src0_sel:WORD_1
	v_cvt_f32_f16_e32 v96, v105
	v_or_b32_e32 v90, 48, v140
	v_mov_b32_e32 v91, v141
	v_lshlrev_b64 v[94:95], 10, v[90:91]
	v_lshl_add_u64 v[94:95], v[94:95], 0, v[138:139]
	v_pk_fma_f32 v[80:81], v[80:81], 0.5, v[96:97] op_sel_hi:[1,0,1]
	v_pk_fma_f32 v[78:79], v[78:79], 0.5, v[92:93] op_sel_hi:[1,0,1]
	s_mov_b64 s[24:25], -1
	s_and_b64 vcc, exec, s[6:7]
	v_lshl_add_u64 v[92:93], v[94:95], 1, s[20:21]
	s_cbranch_vccnz .LBB0_2538
	v_cvt_f16_f32_e32 v96, v78
	v_cvt_f16_f32_sdwa v97, v79 dst_sel:WORD_1 dst_unused:UNUSED_PAD src0_sel:DWORD
	v_cvt_f16_f32_e32 v104, v80
	v_cvt_f16_f32_sdwa v105, v81 dst_sel:WORD_1 dst_unused:UNUSED_PAD src0_sel:DWORD
	s_mov_b64 s[24:25], 0
	v_or_b32_e32 v96, v97, v96
	v_or_b32_e32 v97, v105, v104
	v_mov_b32_e32 v240, v96
	v_mov_b32_e32 v241, v97
	v_pk_mul_f32 v[96:97], v[80:81], v[80:81]
	v_pk_mul_f32 v[104:105], v[78:79], v[78:79]
	s_nop 0
	v_pk_mov_b32 v[106:107], v[104:105], v[96:97] op_sel:[1,0]
	v_mov_b32_e32 v105, v97
	v_pk_add_f32 v[96:97], v[106:107], v[104:105]
	s_nop 0
	v_add_f32_e32 v96, v96, v97

.LBB0_2540:
	s_waitcnt vmcnt(5)
	s_nop 0
	v_cvt_f32_f16_sdwa v79, v102 dst_sel:DWORD dst_unused:UNUSED_PAD src0_sel:WORD_1
	v_cvt_f32_f16_sdwa v81, v103 dst_sel:DWORD dst_unused:UNUSED_PAD src0_sel:WORD_1
	v_cvt_f32_f16_e32 v80, v103
	v_cvt_f32_f16_e32 v78, v102
	s_and_b64 vcc, exec, s[6:7]
	s_mov_b64 s[24:25], -1
	v_pk_fma_f32 v[76:77], v[76:77], 0.5, v[80:81] op_sel_hi:[1,0,1]
	v_pk_fma_f32 v[74:75], v[74:75], 0.5, v[78:79] op_sel_hi:[1,0,1]
	s_cbranch_vccnz .LBB0_2542
	v_cvt_f16_f32_e32 v78, v74
	v_cvt_f16_f32_sdwa v79, v75 dst_sel:WORD_1 dst_unused:UNUSED_PAD src0_sel:DWORD
	v_cvt_f16_f32_e32 v80, v76
	v_cvt_f16_f32_sdwa v81, v77 dst_sel:WORD_1 dst_unused:UNUSED_PAD src0_sel:DWORD
	s_mov_b64 s[24:25], 0
	v_or_b32_e32 v78, v79, v78
	v_or_b32_e32 v79, v81, v80
	v_mov_b32_e32 v242, v78
	v_mov_b32_e32 v243, v79
	v_mbcnt_lo_u32_b32 v222, -1, 0
	v_mbcnt_hi_u32_b32 v222, -1, v222
	v_bfe_u32 v222, v222, 4, 1
	v_mul_u32_u24_e32 v222, 24, v222
	v_mov_b32_e32 v223, 0
	v_permlane16_swap_b32_e32 v240, v242
	v_permlane16_swap_b32_e32 v241, v243
	v_lshl_add_u64 v[222:223], v[92:93], 0, v[222:223]
	global_store_dwordx4 v[222:223], v[240:243], off sc1
	v_pk_mul_f32 v[78:79], v[76:77], v[76:77]
	v_pk_mul_f32 v[80:81], v[74:75], v[74:75]
	s_nop 0
	v_pk_mov_b32 v[102:103], v[80:81], v[78:79] op_sel:[1,0]
	v_mov_b32_e32 v81, v79
	v_pk_add_f32 v[78:79], v[102:103], v[80:81]
	s_nop 0
	v_add_f32_e32 v78, v78, v79
	v_add_f32_e32 v78, v78, v96

.LBB0_2544:
	s_waitcnt vmcnt(4)
	s_nop 0
	v_cvt_f32_f16_sdwa v75, v100 dst_sel:DWORD dst_unused:UNUSED_PAD src0_sel:WORD_1
	v_cvt_f32_f16_sdwa v77, v101 dst_sel:DWORD dst_unused:UNUSED_PAD src0_sel:WORD_1
	v_cvt_f32_f16_e32 v76, v101
	v_cvt_f32_f16_e32 v74, v100
	s_and_b64 vcc, exec, s[6:7]
	s_mov_b64 s[24:25], -1
	v_pk_fma_f32 v[72:73], v[72:73], 0.5, v[76:77] op_sel_hi:[1,0,1]
	v_pk_fma_f32 v[70:71], v[70:71], 0.5, v[74:75] op_sel_hi:[1,0,1]
	s_cbranch_vccnz .LBB0_2546
	v_cvt_f16_f32_e32 v74, v70
	v_cvt_f16_f32_sdwa v75, v71 dst_sel:WORD_1 dst_unused:UNUSED_PAD src0_sel:DWORD
	v_cvt_f16_f32_e32 v76, v72
	v_cvt_f16_f32_sdwa v77, v73 dst_sel:WORD_1 dst_unused:UNUSED_PAD src0_sel:DWORD
	s_mov_b64 s[24:25], 0
	v_or_b32_e32 v74, v75, v74
	v_or_b32_e32 v75, v77, v76
	v_mov_b32_e32 v244, v74
	v_mov_b32_e32 v245, v75
	v_pk_mul_f32 v[74:75], v[72:73], v[72:73]
	v_pk_mul_f32 v[76:77], v[70:71], v[70:71]
	s_nop 0
	v_pk_mov_b32 v[80:81], v[76:77], v[74:75] op_sel:[1,0]
	v_mov_b32_e32 v77, v75
	v_pk_add_f32 v[74:75], v[80:81], v[76:77]
	s_nop 0
	v_add_f32_e32 v74, v74, v75
	v_add_f32_e32 v74, v74, v78

.LBB0_2548:
	s_waitcnt vmcnt(2)
	s_nop 0
	v_cvt_f32_f16_sdwa v71, v98 dst_sel:DWORD dst_unused:UNUSED_PAD src0_sel:WORD_1
	v_cvt_f32_f16_sdwa v73, v99 dst_sel:DWORD dst_unused:UNUSED_PAD src0_sel:WORD_1
	v_cvt_f32_f16_e32 v72, v99
	v_cvt_f32_f16_e32 v70, v98
	s_and_b64 vcc, exec, s[6:7]
	s_mov_b64 s[24:25], -1
	v_pk_fma_f32 v[68:69], v[68:69], 0.5, v[72:73] op_sel_hi:[1,0,1]
	v_pk_fma_f32 v[66:67], v[66:67], 0.5, v[70:71] op_sel_hi:[1,0,1]
	s_cbranch_vccnz .LBB0_2551
	v_cvt_f16_f32_e32 v70, v66
	v_cvt_f16_f32_sdwa v71, v67 dst_sel:WORD_1 dst_unused:UNUSED_PAD src0_sel:DWORD
	v_cvt_f16_f32_sdwa v72, v69 dst_sel:WORD_1 dst_unused:UNUSED_PAD src0_sel:DWORD
	v_or_b32_e32 v70, v71, v70
	v_cvt_f16_f32_e32 v71, v68
	v_or_b32_e32 v71, v72, v71
	v_mov_b32_e32 v246, v70
	v_mov_b32_e32 v247, v71
	v_mbcnt_lo_u32_b32 v222, -1, 0
	v_mbcnt_hi_u32_b32 v222, -1, v222
	v_bfe_u32 v222, v222, 4, 1
	v_mul_u32_u24_e32 v222, 24, v222
	v_mov_b32_e32 v223, 0
	v_permlane16_swap_b32_e32 v244, v246
	v_permlane16_swap_b32_e32 v245, v247
	v_lshl_add_u64 v[222:223], v[92:93], 0, v[222:223]
	global_store_dwordx4 v[222:223], v[244:247], off offset:256 sc1
	v_pk_mul_f32 v[70:71], v[68:69], v[68:69]
	v_pk_mul_f32 v[72:73], v[66:67], v[66:67]
	s_nop 0
	v_pk_mov_b32 v[76:77], v[72:73], v[70:71] op_sel:[1,0]
	v_mov_b32_e32 v73, v71
	v_pk_add_f32 v[70:71], v[76:77], v[72:73]
	s_nop 0
	v_add_f32_e32 v70, v70, v71
	v_add_f32_e32 v70, v70, v74
	s_cbranch_execz .LBB0_2552

.LBB0_2556:
	v_lshl_add_u64 v[76:77], v[140:141], 0, s[96:97]
	s_waitcnt lgkmcnt(0)
	v_lshlrev_b64 v[66:67], 11, v[76:77]
	v_or_b32_e32 v68, 0x8000, v66
	v_mov_b32_e32 v69, v67
	v_lshl_add_u64 v[68:69], v[142:143], 0, v[68:69]
	global_load_dwordx2 v[74:75], v[68:69], off
	global_load_dwordx2 v[72:73], v[68:69], off offset:32
	global_load_dwordx2 v[70:71], v[68:69], off offset:256
	s_nop 0
	global_load_dwordx2 v[68:69], v[68:69], off offset:288
	s_waitcnt vmcnt(6)
	v_cvt_f32_f16_sdwa v79, v88 dst_sel:DWORD dst_unused:UNUSED_PAD src0_sel:WORD_1
	v_cvt_f32_f16_sdwa v91, v89 dst_sel:DWORD dst_unused:UNUSED_PAD src0_sel:WORD_1
	v_cvt_f32_f16_e32 v90, v89
	v_cvt_f32_f16_e32 v78, v88
	v_lshlrev_b64 v[80:81], 10, v[76:77]
	v_lshl_add_u64 v[80:81], v[80:81], 0, v[138:139]
	v_pk_fma_f32 v[64:65], v[64:65], 0.5, v[90:91] op_sel_hi:[1,0,1]
	v_pk_fma_f32 v[62:63], v[62:63], 0.5, v[78:79] op_sel_hi:[1,0,1]
	s_mov_b64 s[24:25], -1
	s_and_b64 vcc, exec, s[6:7]
	v_lshl_add_u64 v[78:79], v[80:81], 1, s[20:21]
	s_cbranch_vccnz .LBB0_2558
	v_cvt_f16_f32_e32 v88, v62
	v_cvt_f16_f32_sdwa v89, v63 dst_sel:WORD_1 dst_unused:UNUSED_PAD src0_sel:DWORD
	v_cvt_f16_f32_e32 v90, v64
	v_cvt_f16_f32_sdwa v91, v65 dst_sel:WORD_1 dst_unused:UNUSED_PAD src0_sel:DWORD
	s_mov_b64 s[24:25], 0
	v_or_b32_e32 v88, v89, v88
	v_or_b32_e32 v89, v91, v90
	v_mov_b32_e32 v240, v88
	v_mov_b32_e32 v241, v89
	v_pk_mul_f32 v[88:89], v[64:65], v[64:65]
	v_pk_mul_f32 v[90:91], v[62:63], v[62:63]
	s_nop 0
	v_pk_mov_b32 v[92:93], v[90:91], v[88:89] op_sel:[1,0]
	v_mov_b32_e32 v91, v89
	v_pk_add_f32 v[88:89], v[92:93], v[90:91]
	s_nop 0
	v_add_f32_e32 v88, v88, v89

.LBB0_2560:
	s_waitcnt vmcnt(5)
	s_nop 0
	v_cvt_f32_f16_sdwa v63, v86 dst_sel:DWORD dst_unused:UNUSED_PAD src0_sel:WORD_1
	v_cvt_f32_f16_sdwa v65, v87 dst_sel:DWORD dst_unused:UNUSED_PAD src0_sel:WORD_1
	v_cvt_f32_f16_e32 v64, v87
	v_cvt_f32_f16_e32 v62, v86
	s_and_b64 vcc, exec, s[6:7]
	s_mov_b64 s[24:25], -1
	v_pk_fma_f32 v[60:61], v[60:61], 0.5, v[64:65] op_sel_hi:[1,0,1]
	v_pk_fma_f32 v[58:59], v[58:59], 0.5, v[62:63] op_sel_hi:[1,0,1]
	s_cbranch_vccnz .LBB0_2562
	v_cvt_f16_f32_e32 v62, v58
	v_cvt_f16_f32_sdwa v63, v59 dst_sel:WORD_1 dst_unused:UNUSED_PAD src0_sel:DWORD
	v_cvt_f16_f32_e32 v64, v60
	v_cvt_f16_f32_sdwa v65, v61 dst_sel:WORD_1 dst_unused:UNUSED_PAD src0_sel:DWORD
	s_mov_b64 s[24:25], 0
	v_or_b32_e32 v62, v63, v62
	v_or_b32_e32 v63, v65, v64
	v_mov_b32_e32 v242, v62
	v_mov_b32_e32 v243, v63
	v_mbcnt_lo_u32_b32 v222, -1, 0
	v_mbcnt_hi_u32_b32 v222, -1, v222
	v_bfe_u32 v222, v222, 4, 1
	v_mul_u32_u24_e32 v222, 24, v222
	v_mov_b32_e32 v223, 0
	v_permlane16_swap_b32_e32 v240, v242
	v_permlane16_swap_b32_e32 v241, v243
	v_lshl_add_u64 v[222:223], v[78:79], 0, v[222:223]
	global_store_dwordx4 v[222:223], v[240:243], off sc1
	v_pk_mul_f32 v[62:63], v[60:61], v[60:61]
	v_pk_mul_f32 v[64:65], v[58:59], v[58:59]
	s_nop 0
	v_pk_mov_b32 v[86:87], v[64:65], v[62:63] op_sel:[1,0]
	v_mov_b32_e32 v65, v63
	v_pk_add_f32 v[62:63], v[86:87], v[64:65]
	s_nop 0
	v_add_f32_e32 v62, v62, v63
	v_add_f32_e32 v62, v62, v88

.LBB0_2564:
	s_waitcnt vmcnt(4)
	s_nop 0
	v_cvt_f32_f16_sdwa v59, v84 dst_sel:DWORD dst_unused:UNUSED_PAD src0_sel:WORD_1
	v_cvt_f32_f16_sdwa v61, v85 dst_sel:DWORD dst_unused:UNUSED_PAD src0_sel:WORD_1
	v_cvt_f32_f16_e32 v60, v85
	v_cvt_f32_f16_e32 v58, v84
	s_and_b64 vcc, exec, s[6:7]
	s_mov_b64 s[24:25], -1
	v_pk_fma_f32 v[56:57], v[56:57], 0.5, v[60:61] op_sel_hi:[1,0,1]
	v_pk_fma_f32 v[54:55], v[54:55], 0.5, v[58:59] op_sel_hi:[1,0,1]
	s_cbranch_vccnz .LBB0_2566
	v_cvt_f16_f32_e32 v58, v54
	v_cvt_f16_f32_sdwa v59, v55 dst_sel:WORD_1 dst_unused:UNUSED_PAD src0_sel:DWORD
	v_cvt_f16_f32_e32 v60, v56
	v_cvt_f16_f32_sdwa v61, v57 dst_sel:WORD_1 dst_unused:UNUSED_PAD src0_sel:DWORD
	s_mov_b64 s[24:25], 0
	v_or_b32_e32 v58, v59, v58
	v_or_b32_e32 v59, v61, v60
	v_mov_b32_e32 v244, v58
	v_mov_b32_e32 v245, v59
	v_pk_mul_f32 v[58:59], v[56:57], v[56:57]
	v_pk_mul_f32 v[60:61], v[54:55], v[54:55]
	s_nop 0
	v_pk_mov_b32 v[64:65], v[60:61], v[58:59] op_sel:[1,0]
	v_mov_b32_e32 v61, v59
	v_pk_add_f32 v[58:59], v[64:65], v[60:61]
	s_nop 0
	v_add_f32_e32 v58, v58, v59
	v_add_f32_e32 v58, v58, v62

.LBB0_2568:
	s_waitcnt vmcnt(2)
	s_nop 0
	v_cvt_f32_f16_sdwa v55, v82 dst_sel:DWORD dst_unused:UNUSED_PAD src0_sel:WORD_1
	v_cvt_f32_f16_sdwa v57, v83 dst_sel:DWORD dst_unused:UNUSED_PAD src0_sel:WORD_1
	v_cvt_f32_f16_e32 v56, v83
	v_cvt_f32_f16_e32 v54, v82
	s_and_b64 vcc, exec, s[6:7]
	s_mov_b64 s[24:25], -1
	v_pk_fma_f32 v[52:53], v[52:53], 0.5, v[56:57] op_sel_hi:[1,0,1]
	v_pk_fma_f32 v[50:51], v[50:51], 0.5, v[54:55] op_sel_hi:[1,0,1]
	s_cbranch_vccnz .LBB0_2571
	v_cvt_f16_f32_e32 v54, v50
	v_cvt_f16_f32_sdwa v55, v51 dst_sel:WORD_1 dst_unused:UNUSED_PAD src0_sel:DWORD
	v_cvt_f16_f32_sdwa v56, v53 dst_sel:WORD_1 dst_unused:UNUSED_PAD src0_sel:DWORD
	v_or_b32_e32 v54, v55, v54
	v_cvt_f16_f32_e32 v55, v52
	v_or_b32_e32 v55, v56, v55
	v_mov_b32_e32 v246, v54
	v_mov_b32_e32 v247, v55
	v_mbcnt_lo_u32_b32 v222, -1, 0
	v_mbcnt_hi_u32_b32 v222, -1, v222
	v_bfe_u32 v222, v222, 4, 1
	v_mul_u32_u24_e32 v222, 24, v222
	v_mov_b32_e32 v223, 0
	v_permlane16_swap_b32_e32 v244, v246
	v_permlane16_swap_b32_e32 v245, v247
	v_lshl_add_u64 v[222:223], v[78:79], 0, v[222:223]
	global_store_dwordx4 v[222:223], v[244:247], off offset:256 sc1
	v_pk_mul_f32 v[54:55], v[52:53], v[52:53]
	v_pk_mul_f32 v[56:57], v[50:51], v[50:51]
	s_nop 0
	v_pk_mov_b32 v[60:61], v[56:57], v[54:55] op_sel:[1,0]
	v_mov_b32_e32 v57, v55
	v_pk_add_f32 v[54:55], v[60:61], v[56:57]
	s_nop 0
	v_add_f32_e32 v54, v54, v55
	v_add_f32_e32 v54, v54, v58
	s_cbranch_execz .LBB0_2572

.LBB0_2576:
	v_or_b32_e32 v50, 0x10000, v66
	s_waitcnt lgkmcnt(0)
	v_mov_b32_e32 v51, v67
	v_lshl_add_u64 v[50:51], v[142:143], 0, v[50:51]
	global_load_dwordx2 v[56:57], v[50:51], off
	global_load_dwordx2 v[54:55], v[50:51], off offset:32
	global_load_dwordx2 v[52:53], v[50:51], off offset:256
	s_nop 0
	global_load_dwordx2 v[50:51], v[50:51], off offset:288
	s_waitcnt vmcnt(6)
	v_cvt_f32_f16_sdwa v61, v74 dst_sel:DWORD dst_unused:UNUSED_PAD src0_sel:WORD_1
	v_cvt_f32_f16_e32 v60, v74
	v_cvt_f32_f16_sdwa v65, v75 dst_sel:DWORD dst_unused:UNUSED_PAD src0_sel:WORD_1
	v_cvt_f32_f16_e32 v64, v75
	s_mov_b64 s[24:25], 0x90
	v_lshl_add_u64 v[58:59], v[140:141], 0, s[24:25]
	v_lshlrev_b64 v[62:63], 10, v[58:59]
	v_lshl_add_u64 v[62:63], v[62:63], 0, v[138:139]
	v_pk_fma_f32 v[48:49], v[48:49], 0.5, v[64:65] op_sel_hi:[1,0,1]
	v_pk_fma_f32 v[46:47], v[46:47], 0.5, v[60:61] op_sel_hi:[1,0,1]
	s_mov_b64 s[24:25], -1
	s_and_b64 vcc, exec, s[6:7]
	v_lshl_add_u64 v[60:61], v[62:63], 1, s[20:21]
	s_cbranch_vccnz .LBB0_2578
	v_cvt_f16_f32_e32 v64, v46
	v_cvt_f16_f32_sdwa v65, v47 dst_sel:WORD_1 dst_unused:UNUSED_PAD src0_sel:DWORD
	v_cvt_f16_f32_e32 v74, v48
	v_cvt_f16_f32_sdwa v75, v49 dst_sel:WORD_1 dst_unused:UNUSED_PAD src0_sel:DWORD
	s_mov_b64 s[24:25], 0
	v_or_b32_e32 v64, v65, v64
	v_or_b32_e32 v65, v75, v74
	v_mov_b32_e32 v240, v64
	v_mov_b32_e32 v241, v65
	v_pk_mul_f32 v[64:65], v[48:49], v[48:49]
	v_pk_mul_f32 v[74:75], v[46:47], v[46:47]
	s_nop 0
	v_pk_mov_b32 v[76:77], v[74:75], v[64:65] op_sel:[1,0]
	v_mov_b32_e32 v75, v65
	v_pk_add_f32 v[64:65], v[76:77], v[74:75]
	s_nop 0
	v_add_f32_e32 v64, v64, v65

.LBB0_2580:
	s_waitcnt vmcnt(5)
	s_nop 0
	v_cvt_f32_f16_sdwa v47, v72 dst_sel:DWORD dst_unused:UNUSED_PAD src0_sel:WORD_1
	v_cvt_f32_f16_sdwa v49, v73 dst_sel:DWORD dst_unused:UNUSED_PAD src0_sel:WORD_1
	v_cvt_f32_f16_e32 v48, v73
	v_cvt_f32_f16_e32 v46, v72
	s_and_b64 vcc, exec, s[6:7]
	s_mov_b64 s[24:25], -1
	v_pk_fma_f32 v[44:45], v[44:45], 0.5, v[48:49] op_sel_hi:[1,0,1]
	v_pk_fma_f32 v[42:43], v[42:43], 0.5, v[46:47] op_sel_hi:[1,0,1]
	s_cbranch_vccnz .LBB0_2582
	v_cvt_f16_f32_e32 v46, v42
	v_cvt_f16_f32_sdwa v47, v43 dst_sel:WORD_1 dst_unused:UNUSED_PAD src0_sel:DWORD
	v_cvt_f16_f32_e32 v48, v44
	v_cvt_f16_f32_sdwa v49, v45 dst_sel:WORD_1 dst_unused:UNUSED_PAD src0_sel:DWORD
	s_mov_b64 s[24:25], 0
	v_or_b32_e32 v46, v47, v46
	v_or_b32_e32 v47, v49, v48
	v_mov_b32_e32 v242, v46
	v_mov_b32_e32 v243, v47
	v_mbcnt_lo_u32_b32 v222, -1, 0
	v_mbcnt_hi_u32_b32 v222, -1, v222
	v_bfe_u32 v222, v222, 4, 1
	v_mul_u32_u24_e32 v222, 24, v222
	v_mov_b32_e32 v223, 0
	v_permlane16_swap_b32_e32 v240, v242
	v_permlane16_swap_b32_e32 v241, v243
	v_lshl_add_u64 v[222:223], v[60:61], 0, v[222:223]
	global_store_dwordx4 v[222:223], v[240:243], off sc1
	v_pk_mul_f32 v[46:47], v[44:45], v[44:45]
	v_pk_mul_f32 v[48:49], v[42:43], v[42:43]
	s_nop 0
	v_pk_mov_b32 v[72:73], v[48:49], v[46:47] op_sel:[1,0]
	v_mov_b32_e32 v49, v47
	v_pk_add_f32 v[46:47], v[72:73], v[48:49]
	s_nop 0
	v_add_f32_e32 v46, v46, v47
	v_add_f32_e32 v46, v46, v64

.LBB0_2584:
	s_waitcnt vmcnt(4)
	s_nop 0
	v_cvt_f32_f16_sdwa v43, v70 dst_sel:DWORD dst_unused:UNUSED_PAD src0_sel:WORD_1
	v_cvt_f32_f16_sdwa v45, v71 dst_sel:DWORD dst_unused:UNUSED_PAD src0_sel:WORD_1
	v_cvt_f32_f16_e32 v44, v71
	v_cvt_f32_f16_e32 v42, v70
	s_and_b64 vcc, exec, s[6:7]
	s_mov_b64 s[24:25], -1
	v_pk_fma_f32 v[40:41], v[40:41], 0.5, v[44:45] op_sel_hi:[1,0,1]
	v_pk_fma_f32 v[38:39], v[38:39], 0.5, v[42:43] op_sel_hi:[1,0,1]
	s_cbranch_vccnz .LBB0_2586
	v_cvt_f16_f32_e32 v42, v38
	v_cvt_f16_f32_sdwa v43, v39 dst_sel:WORD_1 dst_unused:UNUSED_PAD src0_sel:DWORD
	v_cvt_f16_f32_e32 v44, v40
	v_cvt_f16_f32_sdwa v45, v41 dst_sel:WORD_1 dst_unused:UNUSED_PAD src0_sel:DWORD
	s_mov_b64 s[24:25], 0
	v_or_b32_e32 v42, v43, v42
	v_or_b32_e32 v43, v45, v44
	v_mov_b32_e32 v244, v42
	v_mov_b32_e32 v245, v43
	v_pk_mul_f32 v[42:43], v[40:41], v[40:41]
	v_pk_mul_f32 v[44:45], v[38:39], v[38:39]
	s_nop 0
	v_pk_mov_b32 v[48:49], v[44:45], v[42:43] op_sel:[1,0]
	v_mov_b32_e32 v45, v43
	v_pk_add_f32 v[42:43], v[48:49], v[44:45]
	s_nop 0
	v_add_f32_e32 v42, v42, v43
	v_add_f32_e32 v42, v42, v46

.LBB0_2588:
	s_waitcnt vmcnt(2)
	s_nop 0
	v_cvt_f32_f16_sdwa v39, v68 dst_sel:DWORD dst_unused:UNUSED_PAD src0_sel:WORD_1
	v_cvt_f32_f16_sdwa v41, v69 dst_sel:DWORD dst_unused:UNUSED_PAD src0_sel:WORD_1
	v_cvt_f32_f16_e32 v40, v69
	v_cvt_f32_f16_e32 v38, v68
	s_and_b64 vcc, exec, s[6:7]
	s_mov_b64 s[24:25], -1
	v_pk_fma_f32 v[36:37], v[36:37], 0.5, v[40:41] op_sel_hi:[1,0,1]
	v_pk_fma_f32 v[34:35], v[34:35], 0.5, v[38:39] op_sel_hi:[1,0,1]
	s_cbranch_vccnz .LBB0_2591
	v_cvt_f16_f32_e32 v38, v34
	v_cvt_f16_f32_sdwa v39, v35 dst_sel:WORD_1 dst_unused:UNUSED_PAD src0_sel:DWORD
	v_cvt_f16_f32_sdwa v40, v37 dst_sel:WORD_1 dst_unused:UNUSED_PAD src0_sel:DWORD
	v_or_b32_e32 v38, v39, v38
	v_cvt_f16_f32_e32 v39, v36
	v_or_b32_e32 v39, v40, v39
	v_mov_b32_e32 v246, v38
	v_mov_b32_e32 v247, v39
	v_mbcnt_lo_u32_b32 v222, -1, 0
	v_mbcnt_hi_u32_b32 v222, -1, v222
	v_bfe_u32 v222, v222, 4, 1
	v_mul_u32_u24_e32 v222, 24, v222
	v_mov_b32_e32 v223, 0
	v_permlane16_swap_b32_e32 v244, v246
	v_permlane16_swap_b32_e32 v245, v247
	v_lshl_add_u64 v[222:223], v[60:61], 0, v[222:223]
	global_store_dwordx4 v[222:223], v[244:247], off offset:256 sc1
	v_pk_mul_f32 v[38:39], v[36:37], v[36:37]
	v_pk_mul_f32 v[40:41], v[34:35], v[34:35]
	s_nop 0
	v_pk_mov_b32 v[44:45], v[40:41], v[38:39] op_sel:[1,0]
	v_mov_b32_e32 v41, v39
	v_pk_add_f32 v[38:39], v[44:45], v[40:41]
	s_nop 0
	v_add_f32_e32 v38, v38, v39
	v_add_f32_e32 v38, v38, v42
	s_cbranch_execz .LBB0_2592

.LBB0_2596:
	v_or_b32_e32 v66, 0x18000, v66
	s_waitcnt lgkmcnt(0)
	v_lshl_add_u64 v[34:35], v[142:143], 0, v[66:67]
	global_load_dwordx2 v[40:41], v[34:35], off
	global_load_dwordx2 v[38:39], v[34:35], off offset:32
	global_load_dwordx2 v[36:37], v[34:35], off offset:256
	s_nop 0
	global_load_dwordx2 v[34:35], v[34:35], off offset:288
	s_waitcnt vmcnt(6)
	v_cvt_f32_f16_sdwa v45, v56 dst_sel:DWORD dst_unused:UNUSED_PAD src0_sel:WORD_1
	v_cvt_f32_f16_e32 v44, v56
	v_cvt_f32_f16_sdwa v49, v57 dst_sel:DWORD dst_unused:UNUSED_PAD src0_sel:WORD_1
	v_cvt_f32_f16_e32 v48, v57
	s_mov_b64 s[24:25], 0xa0
	v_lshl_add_u64 v[42:43], v[140:141], 0, s[24:25]
	v_lshlrev_b64 v[46:47], 10, v[42:43]
	v_lshl_add_u64 v[46:47], v[46:47], 0, v[138:139]
	v_pk_fma_f32 v[32:33], v[32:33], 0.5, v[48:49] op_sel_hi:[1,0,1]
	v_pk_fma_f32 v[30:31], v[30:31], 0.5, v[44:45] op_sel_hi:[1,0,1]
	s_mov_b64 s[24:25], -1
	s_and_b64 vcc, exec, s[6:7]
	v_lshl_add_u64 v[44:45], v[46:47], 1, s[20:21]
	s_cbranch_vccnz .LBB0_2598
	v_cvt_f16_f32_e32 v48, v30
	v_cvt_f16_f32_sdwa v49, v31 dst_sel:WORD_1 dst_unused:UNUSED_PAD src0_sel:DWORD
	v_cvt_f16_f32_e32 v56, v32
	v_cvt_f16_f32_sdwa v57, v33 dst_sel:WORD_1 dst_unused:UNUSED_PAD src0_sel:DWORD
	s_mov_b64 s[24:25], 0
	v_or_b32_e32 v48, v49, v48
	v_or_b32_e32 v49, v57, v56
	v_mov_b32_e32 v240, v48
	v_mov_b32_e32 v241, v49
	v_pk_mul_f32 v[48:49], v[32:33], v[32:33]
	v_pk_mul_f32 v[56:57], v[30:31], v[30:31]
	s_nop 0
	v_pk_mov_b32 v[58:59], v[56:57], v[48:49] op_sel:[1,0]
	v_mov_b32_e32 v57, v49
	v_pk_add_f32 v[48:49], v[58:59], v[56:57]
	s_nop 0
	v_add_f32_e32 v48, v48, v49

.LBB0_2600:
	s_waitcnt vmcnt(5)
	s_nop 0
	v_cvt_f32_f16_sdwa v31, v54 dst_sel:DWORD dst_unused:UNUSED_PAD src0_sel:WORD_1
	v_cvt_f32_f16_sdwa v33, v55 dst_sel:DWORD dst_unused:UNUSED_PAD src0_sel:WORD_1
	v_cvt_f32_f16_e32 v32, v55
	v_cvt_f32_f16_e32 v30, v54
	s_and_b64 vcc, exec, s[6:7]
	s_mov_b64 s[24:25], -1
	v_pk_fma_f32 v[28:29], v[28:29], 0.5, v[32:33] op_sel_hi:[1,0,1]
	v_pk_fma_f32 v[26:27], v[26:27], 0.5, v[30:31] op_sel_hi:[1,0,1]
	s_cbranch_vccnz .LBB0_2602
	v_cvt_f16_f32_e32 v30, v26
	v_cvt_f16_f32_sdwa v31, v27 dst_sel:WORD_1 dst_unused:UNUSED_PAD src0_sel:DWORD
	v_cvt_f16_f32_e32 v32, v28
	v_cvt_f16_f32_sdwa v33, v29 dst_sel:WORD_1 dst_unused:UNUSED_PAD src0_sel:DWORD
	s_mov_b64 s[24:25], 0
	v_or_b32_e32 v30, v31, v30
	v_or_b32_e32 v31, v33, v32
	v_mov_b32_e32 v242, v30
	v_mov_b32_e32 v243, v31
	v_mbcnt_lo_u32_b32 v222, -1, 0
	v_mbcnt_hi_u32_b32 v222, -1, v222
	v_bfe_u32 v222, v222, 4, 1
	v_mul_u32_u24_e32 v222, 24, v222
	v_mov_b32_e32 v223, 0
	v_permlane16_swap_b32_e32 v240, v242
	v_permlane16_swap_b32_e32 v241, v243
	v_lshl_add_u64 v[222:223], v[44:45], 0, v[222:223]
	global_store_dwordx4 v[222:223], v[240:243], off sc1
	v_pk_mul_f32 v[30:31], v[28:29], v[28:29]
	v_pk_mul_f32 v[32:33], v[26:27], v[26:27]
	s_nop 0
	v_pk_mov_b32 v[54:55], v[32:33], v[30:31] op_sel:[1,0]
	v_mov_b32_e32 v33, v31
	v_pk_add_f32 v[30:31], v[54:55], v[32:33]
	s_nop 0
	v_add_f32_e32 v30, v30, v31
	v_add_f32_e32 v30, v30, v48

.LBB0_2604:
	s_waitcnt vmcnt(4)
	s_nop 0
	v_cvt_f32_f16_sdwa v27, v52 dst_sel:DWORD dst_unused:UNUSED_PAD src0_sel:WORD_1
	v_cvt_f32_f16_sdwa v29, v53 dst_sel:DWORD dst_unused:UNUSED_PAD src0_sel:WORD_1
	v_cvt_f32_f16_e32 v28, v53
	v_cvt_f32_f16_e32 v26, v52
	s_and_b64 vcc, exec, s[6:7]
	s_mov_b64 s[24:25], -1
	v_pk_fma_f32 v[24:25], v[24:25], 0.5, v[28:29] op_sel_hi:[1,0,1]
	v_pk_fma_f32 v[22:23], v[22:23], 0.5, v[26:27] op_sel_hi:[1,0,1]
	s_cbranch_vccnz .LBB0_2606
	v_cvt_f16_f32_e32 v26, v22
	v_cvt_f16_f32_sdwa v27, v23 dst_sel:WORD_1 dst_unused:UNUSED_PAD src0_sel:DWORD
	v_cvt_f16_f32_e32 v28, v24
	v_cvt_f16_f32_sdwa v29, v25 dst_sel:WORD_1 dst_unused:UNUSED_PAD src0_sel:DWORD
	s_mov_b64 s[24:25], 0
	v_or_b32_e32 v26, v27, v26
	v_or_b32_e32 v27, v29, v28
	v_mov_b32_e32 v244, v26
	v_mov_b32_e32 v245, v27
	v_pk_mul_f32 v[26:27], v[24:25], v[24:25]
	v_pk_mul_f32 v[28:29], v[22:23], v[22:23]
	s_nop 0
	v_pk_mov_b32 v[32:33], v[28:29], v[26:27] op_sel:[1,0]
	v_mov_b32_e32 v29, v27
	v_pk_add_f32 v[26:27], v[32:33], v[28:29]
	s_nop 0
	v_add_f32_e32 v26, v26, v27
	v_add_f32_e32 v26, v26, v30

.LBB0_2608:
	s_waitcnt vmcnt(2)
	s_nop 0
	v_cvt_f32_f16_sdwa v23, v50 dst_sel:DWORD dst_unused:UNUSED_PAD src0_sel:WORD_1
	v_cvt_f32_f16_sdwa v25, v51 dst_sel:DWORD dst_unused:UNUSED_PAD src0_sel:WORD_1
	v_cvt_f32_f16_e32 v24, v51
	v_cvt_f32_f16_e32 v22, v50
	s_and_b64 vcc, exec, s[6:7]
	s_mov_b64 s[24:25], -1
	v_pk_fma_f32 v[20:21], v[20:21], 0.5, v[24:25] op_sel_hi:[1,0,1]
	v_pk_fma_f32 v[18:19], v[18:19], 0.5, v[22:23] op_sel_hi:[1,0,1]
	s_cbranch_vccnz .LBB0_2611
	v_cvt_f16_f32_e32 v22, v18
	v_cvt_f16_f32_sdwa v23, v19 dst_sel:WORD_1 dst_unused:UNUSED_PAD src0_sel:DWORD
	v_cvt_f16_f32_sdwa v24, v21 dst_sel:WORD_1 dst_unused:UNUSED_PAD src0_sel:DWORD
	v_or_b32_e32 v22, v23, v22
	v_cvt_f16_f32_e32 v23, v20
	v_or_b32_e32 v23, v24, v23
	v_mov_b32_e32 v246, v22
	v_mov_b32_e32 v247, v23
	v_mbcnt_lo_u32_b32 v222, -1, 0
	v_mbcnt_hi_u32_b32 v222, -1, v222
	v_bfe_u32 v222, v222, 4, 1
	v_mul_u32_u24_e32 v222, 24, v222
	v_mov_b32_e32 v223, 0
	v_permlane16_swap_b32_e32 v244, v246
	v_permlane16_swap_b32_e32 v245, v247
	v_lshl_add_u64 v[222:223], v[44:45], 0, v[222:223]
	global_store_dwordx4 v[222:223], v[244:247], off offset:256 sc1
	v_pk_mul_f32 v[22:23], v[20:21], v[20:21]
	v_pk_mul_f32 v[24:25], v[18:19], v[18:19]
	s_nop 0
	v_pk_mov_b32 v[28:29], v[24:25], v[22:23] op_sel:[1,0]
	v_mov_b32_e32 v25, v23
	v_pk_add_f32 v[22:23], v[28:29], v[24:25]
	s_nop 0
	v_add_f32_e32 v22, v22, v23
	v_add_f32_e32 v22, v22, v26
	s_cbranch_execz .LBB0_2612

.LBB0_2616:
	s_waitcnt vmcnt(2)
	v_cvt_f32_f16_sdwa v21, v40 dst_sel:DWORD dst_unused:UNUSED_PAD src0_sel:WORD_1
	v_cvt_f32_f16_e32 v20, v40
	v_cvt_f32_f16_sdwa v25, v41 dst_sel:DWORD dst_unused:UNUSED_PAD src0_sel:WORD_1
	v_cvt_f32_f16_e32 v24, v41
	s_mov_b64 s[24:25], 0xb0
	s_waitcnt lgkmcnt(0)
	v_lshl_add_u64 v[18:19], v[140:141], 0, s[24:25]
	v_lshlrev_b64 v[22:23], 10, v[18:19]
	v_lshl_add_u64 v[22:23], v[22:23], 0, v[138:139]
	v_pk_fma_f32 v[16:17], v[16:17], 0.5, v[24:25] op_sel_hi:[1,0,1]
	v_pk_fma_f32 v[14:15], v[14:15], 0.5, v[20:21] op_sel_hi:[1,0,1]
	s_mov_b64 s[24:25], -1
	s_and_b64 vcc, exec, s[6:7]
	v_lshl_add_u64 v[20:21], v[22:23], 1, s[20:21]
	s_cbranch_vccnz .LBB0_2618
	v_cvt_f16_f32_e32 v24, v14
	v_cvt_f16_f32_sdwa v25, v15 dst_sel:WORD_1 dst_unused:UNUSED_PAD src0_sel:DWORD
	v_cvt_f16_f32_e32 v26, v16
	v_cvt_f16_f32_sdwa v27, v17 dst_sel:WORD_1 dst_unused:UNUSED_PAD src0_sel:DWORD
	s_mov_b64 s[24:25], 0
	v_or_b32_e32 v24, v25, v24
	v_or_b32_e32 v25, v27, v26
	v_mov_b32_e32 v240, v24
	v_mov_b32_e32 v241, v25
	v_pk_mul_f32 v[24:25], v[16:17], v[16:17]
	v_pk_mul_f32 v[26:27], v[14:15], v[14:15]
	s_nop 0
	v_pk_mov_b32 v[28:29], v[26:27], v[24:25] op_sel:[1,0]
	v_mov_b32_e32 v27, v25
	v_pk_add_f32 v[24:25], v[28:29], v[26:27]
	s_nop 0
	v_add_f32_e32 v24, v24, v25

.LBB0_2620:
	s_waitcnt vmcnt(1)
	s_nop 0
	v_cvt_f32_f16_sdwa v15, v38 dst_sel:DWORD dst_unused:UNUSED_PAD src0_sel:WORD_1
	v_cvt_f32_f16_sdwa v17, v39 dst_sel:DWORD dst_unused:UNUSED_PAD src0_sel:WORD_1
	v_cvt_f32_f16_e32 v16, v39
	v_cvt_f32_f16_e32 v14, v38
	s_and_b64 vcc, exec, s[6:7]
	s_mov_b64 s[20:21], -1
	v_pk_fma_f32 v[12:13], v[12:13], 0.5, v[16:17] op_sel_hi:[1,0,1]
	v_pk_fma_f32 v[10:11], v[10:11], 0.5, v[14:15] op_sel_hi:[1,0,1]
	s_cbranch_vccnz .LBB0_2622
	v_cvt_f16_f32_e32 v14, v10
	v_cvt_f16_f32_sdwa v15, v11 dst_sel:WORD_1 dst_unused:UNUSED_PAD src0_sel:DWORD
	v_cvt_f16_f32_e32 v16, v12
	v_cvt_f16_f32_sdwa v17, v13 dst_sel:WORD_1 dst_unused:UNUSED_PAD src0_sel:DWORD
	s_mov_b64 s[20:21], 0
	v_or_b32_e32 v14, v15, v14
	v_or_b32_e32 v15, v17, v16
	v_mov_b32_e32 v242, v14
	v_mov_b32_e32 v243, v15
	v_mbcnt_lo_u32_b32 v222, -1, 0
	v_mbcnt_hi_u32_b32 v222, -1, v222
	v_bfe_u32 v222, v222, 4, 1
	v_mul_u32_u24_e32 v222, 24, v222
	v_mov_b32_e32 v223, 0
	v_permlane16_swap_b32_e32 v240, v242
	v_permlane16_swap_b32_e32 v241, v243
	v_lshl_add_u64 v[222:223], v[20:21], 0, v[222:223]
	global_store_dwordx4 v[222:223], v[240:243], off sc1
	v_pk_mul_f32 v[14:15], v[12:13], v[12:13]
	v_pk_mul_f32 v[16:17], v[10:11], v[10:11]
	s_nop 0
	v_pk_mov_b32 v[26:27], v[16:17], v[14:15] op_sel:[1,0]
	v_mov_b32_e32 v17, v15
	v_pk_add_f32 v[14:15], v[26:27], v[16:17]
	s_nop 0
	v_add_f32_e32 v14, v14, v15
	v_add_f32_e32 v14, v14, v24

.LBB0_2624:
	s_waitcnt vmcnt(1)
	s_nop 0
	v_cvt_f32_f16_sdwa v11, v36 dst_sel:DWORD dst_unused:UNUSED_PAD src0_sel:WORD_1
	v_cvt_f32_f16_sdwa v13, v37 dst_sel:DWORD dst_unused:UNUSED_PAD src0_sel:WORD_1
	v_cvt_f32_f16_e32 v12, v37
	v_cvt_f32_f16_e32 v10, v36
	s_and_b64 vcc, exec, s[6:7]
	s_mov_b64 s[20:21], -1
	v_pk_fma_f32 v[8:9], v[8:9], 0.5, v[12:13] op_sel_hi:[1,0,1]
	v_pk_fma_f32 v[6:7], v[6:7], 0.5, v[10:11] op_sel_hi:[1,0,1]
	s_cbranch_vccnz .LBB0_2626
	v_cvt_f16_f32_e32 v10, v6
	v_cvt_f16_f32_sdwa v11, v7 dst_sel:WORD_1 dst_unused:UNUSED_PAD src0_sel:DWORD
	v_cvt_f16_f32_e32 v12, v8
	v_cvt_f16_f32_sdwa v13, v9 dst_sel:WORD_1 dst_unused:UNUSED_PAD src0_sel:DWORD
	s_mov_b64 s[20:21], 0
	v_or_b32_e32 v10, v11, v10
	v_or_b32_e32 v11, v13, v12
	v_mov_b32_e32 v244, v10
	v_mov_b32_e32 v245, v11
	v_pk_mul_f32 v[10:11], v[8:9], v[8:9]
	v_pk_mul_f32 v[12:13], v[6:7], v[6:7]
	s_nop 0
	v_pk_mov_b32 v[16:17], v[12:13], v[10:11] op_sel:[1,0]
	v_mov_b32_e32 v13, v11
	v_pk_add_f32 v[10:11], v[16:17], v[12:13]
	s_nop 0
	v_add_f32_e32 v10, v10, v11
	v_add_f32_e32 v10, v10, v14

.LBB0_2628:
	s_waitcnt vmcnt(0)
	s_nop 0
	v_cvt_f32_f16_sdwa v7, v34 dst_sel:DWORD dst_unused:UNUSED_PAD src0_sel:WORD_1
	v_cvt_f32_f16_sdwa v9, v35 dst_sel:DWORD dst_unused:UNUSED_PAD src0_sel:WORD_1
	v_cvt_f32_f16_e32 v8, v35
	v_cvt_f32_f16_e32 v6, v34
	s_and_b64 vcc, exec, s[6:7]
	s_mov_b64 s[20:21], -1
	v_pk_fma_f32 v[4:5], v[4:5], 0.5, v[8:9] op_sel_hi:[1,0,1]
	v_pk_fma_f32 v[2:3], v[2:3], 0.5, v[6:7] op_sel_hi:[1,0,1]
	s_cbranch_vccnz .LBB0_2634
	v_cvt_f16_f32_e32 v6, v2
	v_cvt_f16_f32_sdwa v7, v3 dst_sel:WORD_1 dst_unused:UNUSED_PAD src0_sel:DWORD
	v_cvt_f16_f32_sdwa v8, v5 dst_sel:WORD_1 dst_unused:UNUSED_PAD src0_sel:DWORD
	v_or_b32_e32 v6, v7, v6
	v_cvt_f16_f32_e32 v7, v4
	v_or_b32_e32 v7, v8, v7
	v_mov_b32_e32 v246, v6
	v_mov_b32_e32 v247, v7
	v_mbcnt_lo_u32_b32 v222, -1, 0
	v_mbcnt_hi_u32_b32 v222, -1, v222
	v_bfe_u32 v222, v222, 4, 1
	v_mul_u32_u24_e32 v222, 24, v222
	v_mov_b32_e32 v223, 0
	v_permlane16_swap_b32_e32 v244, v246
	v_permlane16_swap_b32_e32 v245, v247
	v_lshl_add_u64 v[222:223], v[20:21], 0, v[222:223]
	global_store_dwordx4 v[222:223], v[244:247], off offset:256 sc1
	v_pk_mul_f32 v[6:7], v[4:5], v[4:5]
	v_pk_mul_f32 v[8:9], v[2:3], v[2:3]
	s_nop 0
	v_pk_mov_b32 v[12:13], v[8:9], v[6:7] op_sel:[1,0]
	v_mov_b32_e32 v9, v7
	v_pk_add_f32 v[6:7], v[12:13], v[8:9]
	s_nop 0
	v_add_f32_e32 v6, v6, v7
	v_add_f32_e32 v6, v6, v10
	s_cbranch_execz .LBB0_2635
